# work-queue order for the two row-RMSNorm phases after in-place residual GEMMs: most recently written 2048-row chunks first (cache recency)
# speedup vs baseline: 1.0082x; 1.0040x over previous
; #define INP(i) ((const float*)tab_get(lds, (i)))
; #define OUTP() ((float*)tab_get(lds, 30))
; #define WSB(off) ((bf16*)((unsigned char*)tab_get(lds, 31) + (off)))
; #define fresh_lane() (my_tid(lds) & 63)
; #define QNEXT(ctrw, dst) do { __syncthreads(); if (my_tid(lds) == 0) *(volatile LAS int*)(lds + TAB_OFF + 264) = (int)atomicAdd((unsigned*)tab_get(lds, 31) + 8192 + 64 * (ctrw), 1u); \
;         __syncthreads(); dst = __builtin_amdgcn_readfirstlane(*(volatile LAS int*)(lds + TAB_OFF + 264)); } while (0)
; __global__ void __launch_bounds__(512, 2) mega_fwd(Params p) {
;     ...
;     {
;         const int lane = fresh_lane(); const bf16* QC = WSB(WS_QC); bf16* OC = WSB(WS_OCS) - SROWS * DM; const float *c_mk = INP(6), *c_mv = INP(7); const float* X = OUTP(); const float* g = INP(24); bf16* H = WSB(WS_H);
;         for (;;) { int it; QNEXT(3, it); if (it >= 128 + MP / 64) break;
;             if (it < 128) cross_sample_item(lds, QC, c_mk, c_mv, OC, it >> 2, it & 3);
;             else {
; #pragma unroll 1
;                 for (int k = 0; k < 8; k += 2) { const int m = (it - 128) * 64 + wave * 8 + k; rms_row2_to_bf16(X + (size_t)m * DM, X + (size_t)(m + 1) * DM, g, H + (size_t)m * DM, H + (size_t)(m + 1) * DM, lane); } } }
.LBB0_1367:
	s_or_b64 exec, exec, s[4:5]
	s_waitcnt lgkmcnt(0)
	s_barrier
	ds_read_b32 v0, v27
	s_mov_b64 s[4:5], -1
	s_waitcnt lgkmcnt(0)
	v_readfirstlane_b32 s28, v0
	s_cmpk_gt_i32 s28, 0x27f
	s_cbranch_scc1 .LBB0_1364
	s_cmpk_lt_i32 s28, 0x80
	s_cbranch_scc1 .LBB0_1372
	s_sub_i32 s4, s28, 0x80
	s_lshr_b32 s5, s4, 5
	s_and_b32 s14, s4, 31
	s_lshl_b32 s4, s5, 1
	s_or_b32 s4, s4, 1
	s_cmp_lt_u32 s5, 8
	s_cselect_b32 s5, 0, 17
	s_sub_i32 s4, s4, s5
	s_lshl_b32 s4, s4, 5
	s_or_b32 s4, s4, s14
	s_add_i32 s28, s4, 0x80
	s_lshl_b32 s4, s28, 6
	s_add_i32 s4, s20, s4
	s_ashr_i32 s5, s4, 31
	s_lshl_b64 s[14:15], s[4:5], 11
	s_lshl_b64 s[4:5], s[4:5], 12
	v_lshl_add_u64 v[22:23], v[16:17], 0, s[14:15]
	v_lshl_add_u64 v[24:25], v[18:19], 0, s[4:5]
	s_mov_b32 s14, -2

; #define INP(i) ((const float*)tab_get(lds, (i)))
; #define OUTP() ((float*)tab_get(lds, 30))
; #define fresh_lane() (my_tid(lds) & 63)
; #define QNEXT(ctrw, dst) do { __syncthreads(); if (my_tid(lds) == 0) *(volatile LAS int*)(lds + TAB_OFF + 264) = (int)atomicAdd((unsigned*)tab_get(lds, 31) + 8192 + 64 * (ctrw), 1u); \
;         __syncthreads(); dst = __builtin_amdgcn_readfirstlane(*(volatile LAS int*)(lds + TAB_OFF + 264)); } while (0)
; __global__ void __launch_bounds__(512, 2) mega_fwd(Params p) {
;     ...
;         { const int lane = fresh_lane(); float* X = OUTP(); const float* g = INP(29);
;           for (;;) { int it; QNEXT(4, it); if (it >= MP / 64) break;
; #pragma unroll 1
;               for (int k = 0; k < 8; ++k) rms_row_f32_inplace(X + (size_t)(it * 64 + wave * 8 + k) * DM, g, lane); } }
.LBB0_1717:
	s_or_b64 exec, exec, s[2:3]
	s_waitcnt lgkmcnt(0)
	s_barrier
	ds_read_b32 v4, v7
	s_mov_b64 s[2:3], -1
	s_waitcnt lgkmcnt(0)
	v_readfirstlane_b32 s6, v4
	s_cmpk_gt_i32 s6, 0x1ff
	s_cbranch_scc1 .LBB0_1714
	s_lshr_b32 s2, s6, 5
	s_and_b32 s3, s6, 31
	s_lshl_b32 s6, s2, 1
	s_or_b32 s6, s6, 1
	s_cmp_lt_u32 s2, 8
	s_cselect_b32 s2, 0, 17
	s_sub_i32 s6, s6, s2
	s_lshl_b32 s6, s6, 5
	s_or_b32 s6, s6, s3
	s_lshl_b32 s2, s6, 6
	s_add_i32 s2, s2, s70
	s_ashr_i32 s3, s2, 31
	s_lshl_b64 s[2:3], s[2:3], 12
	v_lshl_add_u64 v[4:5], v[2:3], 0, s[2:3]
	s_mov_b64 s[2:3], 0
